# P1 K-loop: LDS-DMA pieces addressed with the scalar base + 32-bit lane offset (no per-piece 64-bit VALU add), as the prologue loads are
# baseline (speedup 1.0000x reference)
; #define PG8_STAGE(bufoff, gbase, voff) do { _Pragma("unroll") for (int _i = 0; _i < 2; ++_i) \
;         __builtin_amdgcn_global_load_lds((const unsigned*)((const char*)(gbase) + (voff)[_i]), (PG8_LAS unsigned*)(lds + (bufoff) + ldsw + _i * 8192), 16, 0, 0); } while (0)
; #define PG8_LDA(dst, b, h) do { _Pragma("unroll") for (int m = 0; m < 4; ++m) _Pragma("unroll") for (int k = 0; k < 2; ++k) dst[m][k] = *(const PG8_LAS bf16x8*)(lds + PG8_SA(b, h) + aoff + m * 2048 + k * 1024); } while (0)
; #define PG8_LDB(dst, b, h) do { _Pragma("unroll") for (int n = 0; n < 2; ++n) _Pragma("unroll") for (int k = 0; k < 2; ++k) dst[n][k] = *(const PG8_LAS bf16x8*)(lds + PG8_SB(b, h) + boff + n * 2048 + k * 1024); } while (0)
; #define PG8_MMA(ai, bj, At, Bt) do { __builtin_amdgcn_s_setprio(1); _Pragma("unroll") for (int m = 0; m < 4; ++m) _Pragma("unroll") for (int n = 0; n < 2; ++n) _Pragma("unroll") for (int k = 0; k < 2; ++k) \
;         acc[ai][bj][m][n] = __builtin_amdgcn_mfma_f32_16x16x32_bf16(Bt[n][k], At[m][k], acc[ai][bj][m][n], 0, 0, 0); __builtin_amdgcn_s_setprio(0); } while (0)
; #define PG8_WAIT_V(n) asm volatile("s_waitcnt vmcnt(" #n ")" ::: "memory")
; #define PG8_WAIT_L(n) asm volatile("s_waitcnt lgkmcnt(" #n ")" ::: "memory")
; #define PG8_BAR __builtin_amdgcn_s_barrier()
; #define PG8_SCHED __builtin_amdgcn_sched_barrier(0)
; template <class Epi, class Sched, bool ALIGN_EPI = false, bool SP2 = false, bool HS = false>
; __device__ __forceinline__ void gemm_phase(PG8_LAS unsigned char* lds, const Gemm g, const Sched& S, const Epi& E) {
;     ...
;             const bool last = (t == nt - 2);
;             const char* a1 = cA + (size_t)(t + 1) * kstep;
;             const char* a2 = last ? nA : cA + (size_t)(t + 2) * kstep; const char* b2 = last ? nB : cB + (size_t)(t + 2) * kstep;
;             const char* a3 = a2 + kstep; const char* b3 = b2 + kstep;
;             if (last && has_next) S.a_ready(nxt);
;             if constexpr (SP2) {
;             PG8_LDB(B0, 0, 0); PG8_LDB(B1, 0, 1); PG8_SCHED; PG8_LDA(At, 0, 0); PG8_STAGE(PG8_SA(1, 1), a1 + hstep, voffA);
;             PG8_WAIT_V(8); PG8_WAIT_L(0); PG8_BAR; PG8_MMA(0, 0, At, B0); PG8_MMA(0, 1, At, B1); PG8_BAR; PG8_SCHED;
;             PG8_LDA(At, 0, 1); PG8_STAGE(PG8_SB(0, 0), b2, voffB); PG8_STAGE(PG8_SB(0, 1), b2 + hstep, voffB); PG8_STAGE(PG8_SA(0, 0), a2, voffA);
.LBB0_261:
	s_ashr_i32 s45, s44, 31
	s_lshl_b64 s[0:1], s[44:45], 19
	s_add_u32 s48, s33, s0
	s_addc_u32 s49, s84, s1
	s_and_b64 s[0:1], s[46:47], exec
	s_cselect_b32 s0, s49, s9
	s_cselect_b32 s1, s48, s8
	s_ashr_i32 s37, s36, 31
	s_lshl_b64 s[52:53], s[36:37], 19
	s_add_u32 s54, s70, s52
	s_addc_u32 s55, s71, s53
	s_and_b64 s[52:53], s[46:47], exec
	s_cselect_b32 s2, s55, s11
	s_cselect_b32 s5, s54, s10
	s_add_u32 s8, s8, 0x40080
	s_addc_u32 s9, s9, 0
	s_add_u32 s7, s10, 0x100
	s_addc_u32 s37, s11, 0
	s_mov_b32 s45, -2
	ds_read_b128 v[4:7], v174
	ds_read_b128 v[12:15], v174 offset:1024
	ds_read_b128 v[136:139], v174 offset:2048
	ds_read_b128 v[140:143], v174 offset:3072
	ds_read_b128 v[158:161], v175
	ds_read_b128 v[162:165], v175 offset:1024
	ds_read_b128 v[182:185], v175 offset:2048
	ds_read_b128 v[188:191], v175 offset:3072
	s_add_u32 s10, s8, 0xfffc0080
	s_addc_u32 s11, s9, -1
	s_cmp_eq_u32 s45, 12
	s_cselect_b32 s57, s0, s11
	s_cselect_b32 s56, s1, s10
	s_cselect_b32 s11, s2, s37
	s_cselect_b32 s10, s5, s7
	s_add_i32 m0, s86, 0xc000
	ds_read_b128 v[192:195], v176
	ds_read_b128 v[196:199], v176 offset:1024
	ds_read_b128 v[200:203], v176 offset:2048
	ds_read_b128 v[204:207], v176 offset:3072
	ds_read_b128 v[208:211], v176 offset:4096
	ds_read_b128 v[212:215], v176 offset:5120
	ds_read_b128 v[216:219], v176 offset:6144
	ds_read_b128 v[220:223], v176 offset:7168
	global_load_lds_dwordx4 v154, s[8:9]
	s_add_i32 m0, s86, 0xe000
	s_nop 0
	global_load_lds_dwordx4 v156, s[8:9]
	s_waitcnt vmcnt(8)
	s_waitcnt lgkmcnt(0)
	s_barrier
	s_setprio 1
	s_waitcnt lgkmcnt(0)
	v_mfma_f32_16x16x32_bf16 v[8:11], v[4:7], v[192:195], 0
	v_mfma_f32_16x16x32_bf16 v[0:3], v[136:139], v[192:195], 0
	v_mfma_f32_16x16x32_bf16 v[124:127], v[4:7], v[200:203], 0
	v_mfma_f32_16x16x32_bf16 v[120:123], v[136:139], v[200:203], 0
	v_mfma_f32_16x16x32_bf16 v[108:111], v[4:7], v[208:211], 0
	v_mfma_f32_16x16x32_bf16 v[104:107], v[136:139], v[208:211], 0
	v_mfma_f32_16x16x32_bf16 v[92:95], v[4:7], v[216:219], 0
	v_mfma_f32_16x16x32_bf16 v[88:91], v[136:139], v[216:219], 0
	v_mfma_f32_16x16x32_bf16 v[8:11], v[12:15], v[196:199], v[8:11]
	v_mfma_f32_16x16x32_bf16 v[0:3], v[140:143], v[196:199], v[0:3]
	v_mfma_f32_16x16x32_bf16 v[124:127], v[12:15], v[204:207], v[124:127]
	v_mfma_f32_16x16x32_bf16 v[120:123], v[140:143], v[204:207], v[120:123]
	v_mfma_f32_16x16x32_bf16 v[108:111], v[12:15], v[212:215], v[108:111]
	v_mfma_f32_16x16x32_bf16 v[104:107], v[140:143], v[212:215], v[104:107]
	v_mfma_f32_16x16x32_bf16 v[92:95], v[12:15], v[220:223], v[92:95]
	v_mfma_f32_16x16x32_bf16 v[88:91], v[140:143], v[220:223], v[88:91]
	s_setprio 0
	s_setprio 1
	v_mfma_f32_16x16x32_bf16 v[132:135], v[158:161], v[192:195], 0
	v_mfma_f32_16x16x32_bf16 v[128:131], v[182:185], v[192:195], 0
	v_mfma_f32_16x16x32_bf16 v[116:119], v[158:161], v[200:203], 0
	v_mfma_f32_16x16x32_bf16 v[112:115], v[182:185], v[200:203], 0
	v_mfma_f32_16x16x32_bf16 v[100:103], v[158:161], v[208:211], 0
	v_mfma_f32_16x16x32_bf16 v[96:99], v[182:185], v[208:211], 0
	v_mfma_f32_16x16x32_bf16 v[84:87], v[158:161], v[216:219], 0
	v_mfma_f32_16x16x32_bf16 v[80:83], v[182:185], v[216:219], 0
	v_mfma_f32_16x16x32_bf16 v[132:135], v[162:165], v[196:199], v[132:135]
	v_mfma_f32_16x16x32_bf16 v[128:131], v[188:191], v[196:199], v[128:131]
	v_mfma_f32_16x16x32_bf16 v[116:119], v[162:165], v[204:207], v[116:119]
	v_mfma_f32_16x16x32_bf16 v[112:115], v[188:191], v[204:207], v[112:115]
	v_mfma_f32_16x16x32_bf16 v[100:103], v[162:165], v[212:215], v[100:103]
	v_mfma_f32_16x16x32_bf16 v[96:99], v[188:191], v[212:215], v[96:99]
	v_mfma_f32_16x16x32_bf16 v[84:87], v[162:165], v[220:223], v[84:87]
	v_mfma_f32_16x16x32_bf16 v[80:83], v[188:191], v[220:223], v[80:83]
	s_setprio 0
	s_barrier
	s_add_i32 s52, s42, s85
	s_mov_b32 m0, s52
	ds_read_b128 v[192:195], v176 offset:16384
	ds_read_b128 v[196:199], v176 offset:17408
	ds_read_b128 v[200:203], v176 offset:18432
	ds_read_b128 v[204:207], v176 offset:19456
	ds_read_b128 v[208:211], v176 offset:20480
	ds_read_b128 v[212:215], v176 offset:21504
	ds_read_b128 v[216:219], v176 offset:22528
	ds_read_b128 v[220:223], v176 offset:23552
	global_load_lds_dwordx4 v146, s[10:11]
	s_add_i32 m0, s52, 0x2000
	s_add_u32 s52, s10, 0x40000
	s_addc_u32 s53, s11, 0
	s_add_i32 s58, s43, s85
	global_load_lds_dwordx4 v150, s[10:11]
	s_mov_b32 m0, s58
	s_nop 0
	global_load_lds_dwordx4 v146, s[52:53]
	s_add_i32 m0, s58, 0x2000
	s_nop 0
	global_load_lds_dwordx4 v150, s[52:53]
	s_mov_b32 m0, s86
	s_nop 0
	global_load_lds_dwordx4 v144, s[56:57]
	s_mov_b32 m0, s87
	s_nop 0
	global_load_lds_dwordx4 v148, s[56:57]
	s_waitcnt vmcnt(8)
	s_waitcnt lgkmcnt(0)
	s_barrier
; #define PG8_STAGE(bufoff, gbase, voff) do { _Pragma("unroll") for (int _i = 0; _i < 2; ++_i) \
;         __builtin_amdgcn_global_load_lds((const unsigned*)((const char*)(gbase) + (voff)[_i]), (PG8_LAS unsigned*)(lds + (bufoff) + ldsw + _i * 8192), 16, 0, 0); } while (0)
; #define PG8_LDA(dst, b, h) do { _Pragma("unroll") for (int m = 0; m < 4; ++m) _Pragma("unroll") for (int k = 0; k < 2; ++k) dst[m][k] = *(const PG8_LAS bf16x8*)(lds + PG8_SA(b, h) + aoff + m * 2048 + k * 1024); } while (0)
; #define PG8_LDB(dst, b, h) do { _Pragma("unroll") for (int n = 0; n < 2; ++n) _Pragma("unroll") for (int k = 0; k < 2; ++k) dst[n][k] = *(const PG8_LAS bf16x8*)(lds + PG8_SB(b, h) + boff + n * 2048 + k * 1024); } while (0)
; #define PG8_MMA(ai, bj, At, Bt) do { __builtin_amdgcn_s_setprio(1); _Pragma("unroll") for (int m = 0; m < 4; ++m) _Pragma("unroll") for (int n = 0; n < 2; ++n) _Pragma("unroll") for (int k = 0; k < 2; ++k) \
;         acc[ai][bj][m][n] = __builtin_amdgcn_mfma_f32_16x16x32_bf16(Bt[n][k], At[m][k], acc[ai][bj][m][n], 0, 0, 0); __builtin_amdgcn_s_setprio(0); } while (0)
; #define PG8_WAIT_V(n) asm volatile("s_waitcnt vmcnt(" #n ")" ::: "memory")
; #define PG8_WAIT_L(n) asm volatile("s_waitcnt lgkmcnt(" #n ")" ::: "memory")
; #define PG8_BAR __builtin_amdgcn_s_barrier()
; #define PG8_SCHED __builtin_amdgcn_sched_barrier(0)
; template <class Epi, class Sched, bool ALIGN_EPI = false, bool SP2 = false, bool HS = false>
; __device__ __forceinline__ void gemm_phase(PG8_LAS unsigned char* lds, const Gemm g, const Sched& S, const Epi& E) {
;     ...
;             PG8_WAIT_V(8); PG8_WAIT_L(0); PG8_BAR; PG8_MMA(1, 0, At, B0); PG8_MMA(1, 1, At, B1); PG8_BAR; PG8_SCHED;
;             PG8_LDB(B0, 1, 0); PG8_LDB(B1, 1, 1); PG8_SCHED; PG8_LDA(At, 1, 0); PG8_STAGE(PG8_SA(0, 1), a2 + hstep, voffA);
;             PG8_WAIT_V(8); PG8_WAIT_L(0); PG8_BAR; PG8_MMA(0, 0, At, B0); PG8_MMA(0, 1, At, B1); PG8_BAR; PG8_SCHED;
	s_setprio 1
	s_waitcnt lgkmcnt(0)
	v_mfma_f32_16x16x32_bf16 v[76:79], v[4:7], v[192:195], 0
	v_mfma_f32_16x16x32_bf16 v[72:75], v[136:139], v[192:195], 0
	v_mfma_f32_16x16x32_bf16 v[60:63], v[4:7], v[200:203], 0
	v_mfma_f32_16x16x32_bf16 v[56:59], v[136:139], v[200:203], 0
	v_mfma_f32_16x16x32_bf16 v[44:47], v[4:7], v[208:211], 0
	v_mfma_f32_16x16x32_bf16 v[40:43], v[136:139], v[208:211], 0
	v_mfma_f32_16x16x32_bf16 v[4:7], v[4:7], v[216:219], 0
	v_mfma_f32_16x16x32_bf16 v[76:79], v[12:15], v[196:199], v[76:79]
	v_mfma_f32_16x16x32_bf16 v[72:75], v[140:143], v[196:199], v[72:75]
	v_mfma_f32_16x16x32_bf16 v[60:63], v[12:15], v[204:207], v[60:63]
	v_mfma_f32_16x16x32_bf16 v[56:59], v[140:143], v[204:207], v[56:59]
	v_mfma_f32_16x16x32_bf16 v[44:47], v[12:15], v[212:215], v[44:47]
	v_mfma_f32_16x16x32_bf16 v[40:43], v[140:143], v[212:215], v[40:43]
	v_mfma_f32_16x16x32_bf16 v[4:7], v[12:15], v[220:223], v[4:7]
	v_mfma_f32_16x16x32_bf16 v[12:15], v[136:139], v[216:219], 0
	v_mfma_f32_16x16x32_bf16 v[12:15], v[140:143], v[220:223], v[12:15]
	s_setprio 0
	s_setprio 1
	v_mfma_f32_16x16x32_bf16 v[24:27], v[158:161], v[192:195], 0
	v_mfma_f32_16x16x32_bf16 v[68:71], v[162:165], v[196:199], v[24:27]
	v_mfma_f32_16x16x32_bf16 v[24:27], v[182:185], v[192:195], 0
	v_mfma_f32_16x16x32_bf16 v[64:67], v[188:191], v[196:199], v[24:27]
	v_mfma_f32_16x16x32_bf16 v[24:27], v[158:161], v[200:203], 0
	v_mfma_f32_16x16x32_bf16 v[52:55], v[162:165], v[204:207], v[24:27]
	v_mfma_f32_16x16x32_bf16 v[24:27], v[182:185], v[200:203], 0
	v_mfma_f32_16x16x32_bf16 v[48:51], v[188:191], v[204:207], v[24:27]
	v_mfma_f32_16x16x32_bf16 v[24:27], v[158:161], v[208:211], 0
	v_mfma_f32_16x16x32_bf16 v[36:39], v[162:165], v[212:215], v[24:27]
	v_mfma_f32_16x16x32_bf16 v[24:27], v[182:185], v[208:211], 0
	v_mfma_f32_16x16x32_bf16 v[20:23], v[158:161], v[216:219], 0
	v_mfma_f32_16x16x32_bf16 v[16:19], v[182:185], v[216:219], 0
	v_mfma_f32_16x16x32_bf16 v[32:35], v[188:191], v[212:215], v[24:27]
	v_mfma_f32_16x16x32_bf16 v[20:23], v[162:165], v[220:223], v[20:23]
	v_mfma_f32_16x16x32_bf16 v[16:19], v[188:191], v[220:223], v[16:19]
	s_setprio 0
	s_barrier
	s_add_i32 s58, 0, 0x18000
	s_add_i32 s59, 0, 0x1c000
	v_add_u32_e32 v140, s58, v169
	v_add_u32_e32 v152, s59, v169
	ds_read_b128 v[24:27], v140
	ds_read_b128 v[28:31], v140 offset:1024
	ds_read_b128 v[136:139], v140 offset:2048
	ds_read_b128 v[140:143], v140 offset:3072
	ds_read_b128 v[158:161], v152
	ds_read_b128 v[162:165], v152 offset:1024
	ds_read_b128 v[182:185], v152 offset:2048
	ds_read_b128 v[188:191], v152 offset:3072
	s_add_u32 s52, s56, 0x40000
	s_addc_u32 s53, s57, 0
	s_mov_b32 m0, s88
	ds_read_b128 v[192:195], v176 offset:32768
	ds_read_b128 v[196:199], v176 offset:33792
	ds_read_b128 v[200:203], v176 offset:34816
	ds_read_b128 v[204:207], v176 offset:35840
	ds_read_b128 v[208:211], v176 offset:36864
	ds_read_b128 v[212:215], v176 offset:37888
	ds_read_b128 v[216:219], v176 offset:38912
	ds_read_b128 v[220:223], v176 offset:39936
	global_load_lds_dwordx4 v144, s[52:53]
	s_mov_b32 m0, s89
	s_nop 0
	global_load_lds_dwordx4 v148, s[52:53]
	s_waitcnt vmcnt(8)
	s_waitcnt lgkmcnt(0)
	s_barrier
	s_setprio 1
	s_waitcnt lgkmcnt(0)
	v_mfma_f32_16x16x32_bf16 v[8:11], v[24:27], v[192:195], v[8:11]
	v_mfma_f32_16x16x32_bf16 v[0:3], v[136:139], v[192:195], v[0:3]
	v_mfma_f32_16x16x32_bf16 v[124:127], v[24:27], v[200:203], v[124:127]
	v_mfma_f32_16x16x32_bf16 v[120:123], v[136:139], v[200:203], v[120:123]
	v_mfma_f32_16x16x32_bf16 v[108:111], v[24:27], v[208:211], v[108:111]
	v_mfma_f32_16x16x32_bf16 v[104:107], v[136:139], v[208:211], v[104:107]
	v_mfma_f32_16x16x32_bf16 v[92:95], v[24:27], v[216:219], v[92:95]
	v_mfma_f32_16x16x32_bf16 v[88:91], v[136:139], v[216:219], v[88:91]
	v_mfma_f32_16x16x32_bf16 v[8:11], v[28:31], v[196:199], v[8:11]
	v_mfma_f32_16x16x32_bf16 v[0:3], v[140:143], v[196:199], v[0:3]
	v_mfma_f32_16x16x32_bf16 v[124:127], v[28:31], v[204:207], v[124:127]
	v_mfma_f32_16x16x32_bf16 v[120:123], v[140:143], v[204:207], v[120:123]
	v_mfma_f32_16x16x32_bf16 v[108:111], v[28:31], v[212:215], v[108:111]
	v_mfma_f32_16x16x32_bf16 v[104:107], v[140:143], v[212:215], v[104:107]
	v_mfma_f32_16x16x32_bf16 v[92:95], v[28:31], v[220:223], v[92:95]
	v_mfma_f32_16x16x32_bf16 v[88:91], v[140:143], v[220:223], v[88:91]
	s_setprio 0
	s_setprio 1
	v_mfma_f32_16x16x32_bf16 v[132:135], v[158:161], v[192:195], v[132:135]
	v_mfma_f32_16x16x32_bf16 v[128:131], v[182:185], v[192:195], v[128:131]
	v_mfma_f32_16x16x32_bf16 v[116:119], v[158:161], v[200:203], v[116:119]
	v_mfma_f32_16x16x32_bf16 v[112:115], v[182:185], v[200:203], v[112:115]
	v_mfma_f32_16x16x32_bf16 v[100:103], v[158:161], v[208:211], v[100:103]
	v_mfma_f32_16x16x32_bf16 v[96:99], v[182:185], v[208:211], v[96:99]
	v_mfma_f32_16x16x32_bf16 v[84:87], v[158:161], v[216:219], v[84:87]
	v_mfma_f32_16x16x32_bf16 v[80:83], v[182:185], v[216:219], v[80:83]
	v_mfma_f32_16x16x32_bf16 v[132:135], v[162:165], v[196:199], v[132:135]
	v_mfma_f32_16x16x32_bf16 v[128:131], v[188:191], v[196:199], v[128:131]
	v_mfma_f32_16x16x32_bf16 v[116:119], v[162:165], v[204:207], v[116:119]
	v_mfma_f32_16x16x32_bf16 v[112:115], v[188:191], v[204:207], v[112:115]
	v_mfma_f32_16x16x32_bf16 v[100:103], v[162:165], v[212:215], v[100:103]
	v_mfma_f32_16x16x32_bf16 v[96:99], v[188:191], v[212:215], v[96:99]
	v_mfma_f32_16x16x32_bf16 v[84:87], v[162:165], v[220:223], v[84:87]
	v_mfma_f32_16x16x32_bf16 v[80:83], v[188:191], v[220:223], v[80:83]
	s_setprio 0
	s_barrier
; #define PG8_STAGE(bufoff, gbase, voff) do { _Pragma("unroll") for (int _i = 0; _i < 2; ++_i) \
;         __builtin_amdgcn_global_load_lds((const unsigned*)((const char*)(gbase) + (voff)[_i]), (PG8_LAS unsigned*)(lds + (bufoff) + ldsw + _i * 8192), 16, 0, 0); } while (0)
; #define PG8_LDA(dst, b, h) do { _Pragma("unroll") for (int m = 0; m < 4; ++m) _Pragma("unroll") for (int k = 0; k < 2; ++k) dst[m][k] = *(const PG8_LAS bf16x8*)(lds + PG8_SA(b, h) + aoff + m * 2048 + k * 1024); } while (0)
; #define PG8_LDB(dst, b, h) do { _Pragma("unroll") for (int n = 0; n < 2; ++n) _Pragma("unroll") for (int k = 0; k < 2; ++k) dst[n][k] = *(const PG8_LAS bf16x8*)(lds + PG8_SB(b, h) + boff + n * 2048 + k * 1024); } while (0)
; #define PG8_WAIT_V(n) asm volatile("s_waitcnt vmcnt(" #n ")" ::: "memory")
; template <class Epi, class Sched, bool ALIGN_EPI = false, bool SP2 = false, bool HS = false>
; __device__ __forceinline__ void gemm_phase(PG8_LAS unsigned char* lds, const Gemm g, const Sched& S, const Epi& E) {
;     ...
;             const char* a1 = cA + (size_t)(t + 1) * kstep;
;             const char* a2 = last ? nA : cA + (size_t)(t + 2) * kstep; const char* b2 = last ? nB : cB + (size_t)(t + 2) * kstep;
;             const char* a3 = a2 + kstep; const char* b3 = b2 + kstep;
;             if (last && has_next) S.a_ready(nxt);
;             if constexpr (SP2) {
;             PG8_LDB(B0, 0, 0); PG8_LDB(B1, 0, 1); PG8_SCHED; PG8_LDA(At, 0, 0); PG8_STAGE(PG8_SA(1, 1), a1 + hstep, voffA);
;             PG8_WAIT_V(8); PG8_WAIT_L(0); PG8_BAR; PG8_MMA(0, 0, At, B0); PG8_MMA(0, 1, At, B1); PG8_BAR; PG8_SCHED;
;             PG8_LDA(At, 0, 1); PG8_STAGE(PG8_SB(0, 0), b2, voffB); PG8_STAGE(PG8_SB(0, 1), b2 + hstep, voffB); PG8_STAGE(PG8_SA(0, 0), a2, voffA);
;             PG8_WAIT_V(8); PG8_WAIT_L(0); PG8_BAR; PG8_MMA(1, 0, At, B0); PG8_MMA(1, 1, At, B1); PG8_BAR; PG8_SCHED;
;             PG8_LDB(B0, 1, 0); PG8_LDB(B1, 1, 1); PG8_SCHED; PG8_LDA(At, 1, 0); PG8_STAGE(PG8_SA(0, 1), a2 + hstep, voffA);
;             PG8_WAIT_V(8); PG8_WAIT_L(0); PG8_BAR; PG8_MMA(0, 0, At, B0); PG8_MMA(0, 1, At, B1); PG8_BAR; PG8_SCHED;
;             PG8_LDA(At, 1, 1); PG8_STAGE(PG8_SB(1, 0), b3, voffB); PG8_STAGE(PG8_SB(1, 1), b3 + hstep, voffB); PG8_STAGE(PG8_SA(1, 0), a3, voffA);
;             PG8_WAIT_V(8); PG8_WAIT_L(0); PG8_BAR; PG8_MMA(1, 0, At, B0); PG8_MMA(1, 1, At, B1); PG8_BAR; PG8_SCHED;
	s_add_i32 s52, s58, s85
	s_mov_b32 m0, s52
	ds_read_b128 v[192:195], v176 offset:49152
	ds_read_b128 v[196:199], v176 offset:50176
	ds_read_b128 v[200:203], v176 offset:51200
	ds_read_b128 v[204:207], v176 offset:52224
	ds_read_b128 v[208:211], v176 offset:53248
	ds_read_b128 v[212:215], v176 offset:54272
	ds_read_b128 v[216:219], v176 offset:55296
	ds_read_b128 v[220:223], v176 offset:56320
	s_add_u32 s98, s10, 0x80
	s_addc_u32 s99, s11, 0
	global_load_lds_dwordx4 v146, s[98:99]
	s_add_i32 m0, s52, 0x2000
	s_add_u32 s10, s10, 0x40080
	s_addc_u32 s11, s11, 0
	s_add_i32 s52, s59, s85
	global_load_lds_dwordx4 v150, s[98:99]
	s_mov_b32 m0, s52
	s_nop 0
	global_load_lds_dwordx4 v146, s[10:11]
	s_add_i32 m0, s52, 0x2000
	s_nop 0
	global_load_lds_dwordx4 v150, s[10:11]
	s_mov_b32 m0, s95
	s_nop 0
	s_add_u32 s98, s56, 0x80
	s_addc_u32 s99, s57, 0
	global_load_lds_dwordx4 v144, s[98:99]
	s_mov_b32 m0, s96
	s_nop 0
	global_load_lds_dwordx4 v148, s[98:99]
	s_waitcnt vmcnt(8)
	s_waitcnt lgkmcnt(0)
	s_barrier
	s_setprio 1
	s_waitcnt lgkmcnt(0)
	v_mfma_f32_16x16x32_bf16 v[76:79], v[24:27], v[192:195], v[76:79]
	v_mfma_f32_16x16x32_bf16 v[60:63], v[24:27], v[200:203], v[60:63]
	v_mfma_f32_16x16x32_bf16 v[44:47], v[24:27], v[208:211], v[44:47]
	v_mfma_f32_16x16x32_bf16 v[4:7], v[24:27], v[216:219], v[4:7]
	v_mfma_f32_16x16x32_bf16 v[76:79], v[28:31], v[196:199], v[76:79]
	v_mfma_f32_16x16x32_bf16 v[72:75], v[136:139], v[192:195], v[72:75]
	v_mfma_f32_16x16x32_bf16 v[60:63], v[28:31], v[204:207], v[60:63]
	v_mfma_f32_16x16x32_bf16 v[56:59], v[136:139], v[200:203], v[56:59]
	v_mfma_f32_16x16x32_bf16 v[44:47], v[28:31], v[212:215], v[44:47]
	v_mfma_f32_16x16x32_bf16 v[40:43], v[136:139], v[208:211], v[40:43]
	v_mfma_f32_16x16x32_bf16 v[28:31], v[28:31], v[220:223], v[4:7]
	v_mfma_f32_16x16x32_bf16 v[4:7], v[136:139], v[216:219], v[12:15]
	v_mfma_f32_16x16x32_bf16 v[72:75], v[140:143], v[196:199], v[72:75]
	v_mfma_f32_16x16x32_bf16 v[56:59], v[140:143], v[204:207], v[56:59]
	v_mfma_f32_16x16x32_bf16 v[40:43], v[140:143], v[212:215], v[40:43]
	v_mfma_f32_16x16x32_bf16 v[24:27], v[140:143], v[220:223], v[4:7]
	s_setprio 0
	s_setprio 1
	v_mfma_f32_16x16x32_bf16 v[4:7], v[158:161], v[192:195], v[68:71]
	v_mfma_f32_16x16x32_bf16 v[68:71], v[162:165], v[196:199], v[4:7]
	v_mfma_f32_16x16x32_bf16 v[4:7], v[182:185], v[192:195], v[64:67]
	v_mfma_f32_16x16x32_bf16 v[64:67], v[188:191], v[196:199], v[4:7]
	v_mfma_f32_16x16x32_bf16 v[4:7], v[158:161], v[200:203], v[52:55]
	v_mfma_f32_16x16x32_bf16 v[52:55], v[162:165], v[204:207], v[4:7]
	v_mfma_f32_16x16x32_bf16 v[4:7], v[182:185], v[200:203], v[48:51]
	v_mfma_f32_16x16x32_bf16 v[48:51], v[188:191], v[204:207], v[4:7]
	v_mfma_f32_16x16x32_bf16 v[4:7], v[158:161], v[208:211], v[36:39]
	v_mfma_f32_16x16x32_bf16 v[36:39], v[162:165], v[212:215], v[4:7]
	v_mfma_f32_16x16x32_bf16 v[4:7], v[182:185], v[208:211], v[32:35]
	v_mfma_f32_16x16x32_bf16 v[32:35], v[188:191], v[212:215], v[4:7]
	v_mfma_f32_16x16x32_bf16 v[4:7], v[158:161], v[216:219], v[20:23]
	v_mfma_f32_16x16x32_bf16 v[20:23], v[162:165], v[220:223], v[4:7]
	v_mfma_f32_16x16x32_bf16 v[4:7], v[182:185], v[216:219], v[16:19]
	v_mfma_f32_16x16x32_bf16 v[16:19], v[188:191], v[220:223], v[4:7]
	s_setprio 0
	s_barrier
	s_add_i32 s45, s45, 2
	s_add_u32 s8, s8, 0x100
	s_addc_u32 s9, s9, 0
	s_add_u32 s7, s7, 0x100
	s_addc_u32 s37, s37, 0
	s_cmp_gt_u32 s45, 13
.LBB0_262:
	ds_read_b128 v[4:7], v174
	ds_read_b128 v[12:15], v174 offset:1024
	ds_read_b128 v[136:139], v174 offset:2048
	ds_read_b128 v[140:143], v174 offset:3072
	ds_read_b128 v[158:161], v175
	ds_read_b128 v[162:165], v175 offset:1024
	ds_read_b128 v[182:185], v175 offset:2048
	ds_read_b128 v[188:191], v175 offset:3072
	s_add_u32 s10, s8, 0xfffc0080
	s_addc_u32 s11, s9, -1
	s_cmp_eq_u32 s45, 12
	s_cselect_b32 s57, s0, s11
	s_cselect_b32 s56, s1, s10
	s_cselect_b32 s11, s2, s37
	s_cselect_b32 s10, s5, s7
	s_add_i32 m0, s86, 0xc000
	ds_read_b128 v[192:195], v176
	ds_read_b128 v[196:199], v176 offset:1024
	ds_read_b128 v[200:203], v176 offset:2048
	ds_read_b128 v[204:207], v176 offset:3072
	ds_read_b128 v[208:211], v176 offset:4096
	ds_read_b128 v[212:215], v176 offset:5120
	ds_read_b128 v[216:219], v176 offset:6144
	ds_read_b128 v[220:223], v176 offset:7168
	global_load_lds_dwordx4 v154, s[8:9]
	s_add_i32 m0, s86, 0xe000
	s_nop 0
	global_load_lds_dwordx4 v156, s[8:9]
	s_waitcnt vmcnt(8)
	s_waitcnt lgkmcnt(0)
	s_barrier
	s_setprio 1
	s_waitcnt lgkmcnt(0)
	v_mfma_f32_16x16x32_bf16 v[8:11], v[4:7], v[192:195], v[8:11]
	v_mfma_f32_16x16x32_bf16 v[0:3], v[136:139], v[192:195], v[0:3]
	v_mfma_f32_16x16x32_bf16 v[124:127], v[4:7], v[200:203], v[124:127]
	v_mfma_f32_16x16x32_bf16 v[120:123], v[136:139], v[200:203], v[120:123]
	v_mfma_f32_16x16x32_bf16 v[108:111], v[4:7], v[208:211], v[108:111]
	v_mfma_f32_16x16x32_bf16 v[104:107], v[136:139], v[208:211], v[104:107]
	v_mfma_f32_16x16x32_bf16 v[92:95], v[4:7], v[216:219], v[92:95]
	v_mfma_f32_16x16x32_bf16 v[88:91], v[136:139], v[216:219], v[88:91]
	v_mfma_f32_16x16x32_bf16 v[8:11], v[12:15], v[196:199], v[8:11]
	v_mfma_f32_16x16x32_bf16 v[0:3], v[140:143], v[196:199], v[0:3]
	v_mfma_f32_16x16x32_bf16 v[124:127], v[12:15], v[204:207], v[124:127]
	v_mfma_f32_16x16x32_bf16 v[120:123], v[140:143], v[204:207], v[120:123]
	v_mfma_f32_16x16x32_bf16 v[108:111], v[12:15], v[212:215], v[108:111]
	v_mfma_f32_16x16x32_bf16 v[104:107], v[140:143], v[212:215], v[104:107]
	v_mfma_f32_16x16x32_bf16 v[92:95], v[12:15], v[220:223], v[92:95]
	v_mfma_f32_16x16x32_bf16 v[88:91], v[140:143], v[220:223], v[88:91]
	s_setprio 0
	s_setprio 1
	v_mfma_f32_16x16x32_bf16 v[132:135], v[158:161], v[192:195], v[132:135]
	v_mfma_f32_16x16x32_bf16 v[128:131], v[182:185], v[192:195], v[128:131]
	v_mfma_f32_16x16x32_bf16 v[116:119], v[158:161], v[200:203], v[116:119]
	v_mfma_f32_16x16x32_bf16 v[112:115], v[182:185], v[200:203], v[112:115]
	v_mfma_f32_16x16x32_bf16 v[100:103], v[158:161], v[208:211], v[100:103]
	v_mfma_f32_16x16x32_bf16 v[96:99], v[182:185], v[208:211], v[96:99]
	v_mfma_f32_16x16x32_bf16 v[84:87], v[158:161], v[216:219], v[84:87]
	v_mfma_f32_16x16x32_bf16 v[80:83], v[182:185], v[216:219], v[80:83]
	v_mfma_f32_16x16x32_bf16 v[132:135], v[162:165], v[196:199], v[132:135]
	v_mfma_f32_16x16x32_bf16 v[128:131], v[188:191], v[196:199], v[128:131]
	v_mfma_f32_16x16x32_bf16 v[116:119], v[162:165], v[204:207], v[116:119]
	v_mfma_f32_16x16x32_bf16 v[112:115], v[188:191], v[204:207], v[112:115]
	v_mfma_f32_16x16x32_bf16 v[100:103], v[162:165], v[212:215], v[100:103]
	v_mfma_f32_16x16x32_bf16 v[96:99], v[188:191], v[212:215], v[96:99]
	v_mfma_f32_16x16x32_bf16 v[84:87], v[162:165], v[220:223], v[84:87]
	v_mfma_f32_16x16x32_bf16 v[80:83], v[188:191], v[220:223], v[80:83]
	s_setprio 0
	s_barrier
; #define PG8_STAGE(bufoff, gbase, voff) do { _Pragma("unroll") for (int _i = 0; _i < 2; ++_i) \
;         __builtin_amdgcn_global_load_lds((const unsigned*)((const char*)(gbase) + (voff)[_i]), (PG8_LAS unsigned*)(lds + (bufoff) + ldsw + _i * 8192), 16, 0, 0); } while (0)
; #define PG8_LDA(dst, b, h) do { _Pragma("unroll") for (int m = 0; m < 4; ++m) _Pragma("unroll") for (int k = 0; k < 2; ++k) dst[m][k] = *(const PG8_LAS bf16x8*)(lds + PG8_SA(b, h) + aoff + m * 2048 + k * 1024); } while (0)
; #define PG8_LDB(dst, b, h) do { _Pragma("unroll") for (int n = 0; n < 2; ++n) _Pragma("unroll") for (int k = 0; k < 2; ++k) dst[n][k] = *(const PG8_LAS bf16x8*)(lds + PG8_SB(b, h) + boff + n * 2048 + k * 1024); } while (0)
; #define PG8_MMA(ai, bj, At, Bt) do { __builtin_amdgcn_s_setprio(1); _Pragma("unroll") for (int m = 0; m < 4; ++m) _Pragma("unroll") for (int n = 0; n < 2; ++n) _Pragma("unroll") for (int k = 0; k < 2; ++k) \
;         acc[ai][bj][m][n] = __builtin_amdgcn_mfma_f32_16x16x32_bf16(Bt[n][k], At[m][k], acc[ai][bj][m][n], 0, 0, 0); __builtin_amdgcn_s_setprio(0); } while (0)
; template <class Epi, class Sched, bool ALIGN_EPI = false, bool SP2 = false, bool HS = false>
; __device__ __forceinline__ void gemm_phase(PG8_LAS unsigned char* lds, const Gemm g, const Sched& S, const Epi& E) {
;     ...
;             if constexpr (SP2) {
;             PG8_LDB(B0, 0, 0); PG8_LDB(B1, 0, 1); PG8_SCHED; PG8_LDA(At, 0, 0); PG8_STAGE(PG8_SA(1, 1), a1 + hstep, voffA);
;             PG8_WAIT_V(8); PG8_WAIT_L(0); PG8_BAR; PG8_MMA(0, 0, At, B0); PG8_MMA(0, 1, At, B1); PG8_BAR; PG8_SCHED;
;             PG8_LDA(At, 0, 1); PG8_STAGE(PG8_SB(0, 0), b2, voffB); PG8_STAGE(PG8_SB(0, 1), b2 + hstep, voffB); PG8_STAGE(PG8_SA(0, 0), a2, voffA);
;             PG8_WAIT_V(8); PG8_WAIT_L(0); PG8_BAR; PG8_MMA(1, 0, At, B0); PG8_MMA(1, 1, At, B1); PG8_BAR; PG8_SCHED;
;             PG8_LDB(B0, 1, 0); PG8_LDB(B1, 1, 1); PG8_SCHED; PG8_LDA(At, 1, 0); PG8_STAGE(PG8_SA(0, 1), a2 + hstep, voffA);
;             PG8_WAIT_V(8); PG8_WAIT_L(0); PG8_BAR; PG8_MMA(0, 0, At, B0); PG8_MMA(0, 1, At, B1); PG8_BAR; PG8_SCHED;
;             PG8_LDA(At, 1, 1); PG8_STAGE(PG8_SB(1, 0), b3, voffB); PG8_STAGE(PG8_SB(1, 1), b3 + hstep, voffB); PG8_STAGE(PG8_SA(1, 0), a3, voffA);
;             PG8_WAIT_V(8); PG8_WAIT_L(0); PG8_BAR; PG8_MMA(1, 0, At, B0); PG8_MMA(1, 1, At, B1); PG8_BAR; PG8_SCHED;
	s_add_i32 s52, s42, s85
	s_mov_b32 m0, s52
	ds_read_b128 v[192:195], v176 offset:16384
	ds_read_b128 v[196:199], v176 offset:17408
	ds_read_b128 v[200:203], v176 offset:18432
	ds_read_b128 v[204:207], v176 offset:19456
	ds_read_b128 v[208:211], v176 offset:20480
	ds_read_b128 v[212:215], v176 offset:21504
	ds_read_b128 v[216:219], v176 offset:22528
	ds_read_b128 v[220:223], v176 offset:23552
	global_load_lds_dwordx4 v146, s[10:11]
	s_add_i32 m0, s52, 0x2000
	s_add_u32 s52, s10, 0x40000
	s_addc_u32 s53, s11, 0
	s_add_i32 s58, s43, s85
	global_load_lds_dwordx4 v150, s[10:11]
	s_mov_b32 m0, s58
	s_nop 0
	global_load_lds_dwordx4 v146, s[52:53]
	s_add_i32 m0, s58, 0x2000
	s_nop 0
	global_load_lds_dwordx4 v150, s[52:53]
	s_mov_b32 m0, s86
	s_nop 0
	global_load_lds_dwordx4 v144, s[56:57]
	s_mov_b32 m0, s87
	s_nop 0
	global_load_lds_dwordx4 v148, s[56:57]
	s_waitcnt vmcnt(8)
	s_waitcnt lgkmcnt(0)
	s_barrier
	s_setprio 1
	s_waitcnt lgkmcnt(0)
	v_mfma_f32_16x16x32_bf16 v[76:79], v[4:7], v[192:195], v[76:79]
	v_mfma_f32_16x16x32_bf16 v[72:75], v[136:139], v[192:195], v[72:75]
	v_mfma_f32_16x16x32_bf16 v[60:63], v[4:7], v[200:203], v[60:63]
	v_mfma_f32_16x16x32_bf16 v[56:59], v[136:139], v[200:203], v[56:59]
	v_mfma_f32_16x16x32_bf16 v[44:47], v[4:7], v[208:211], v[44:47]
	v_mfma_f32_16x16x32_bf16 v[40:43], v[136:139], v[208:211], v[40:43]
	v_mfma_f32_16x16x32_bf16 v[4:7], v[4:7], v[216:219], v[28:31]
	v_mfma_f32_16x16x32_bf16 v[76:79], v[12:15], v[196:199], v[76:79]
	v_mfma_f32_16x16x32_bf16 v[72:75], v[140:143], v[196:199], v[72:75]
	v_mfma_f32_16x16x32_bf16 v[60:63], v[12:15], v[204:207], v[60:63]
	v_mfma_f32_16x16x32_bf16 v[56:59], v[140:143], v[204:207], v[56:59]
	v_mfma_f32_16x16x32_bf16 v[44:47], v[12:15], v[212:215], v[44:47]
	v_mfma_f32_16x16x32_bf16 v[40:43], v[140:143], v[212:215], v[40:43]
	v_mfma_f32_16x16x32_bf16 v[4:7], v[12:15], v[220:223], v[4:7]
	v_mfma_f32_16x16x32_bf16 v[12:15], v[136:139], v[216:219], v[24:27]
	v_mfma_f32_16x16x32_bf16 v[12:15], v[140:143], v[220:223], v[12:15]
	s_setprio 0
	s_setprio 1
	v_mfma_f32_16x16x32_bf16 v[24:27], v[158:161], v[192:195], v[68:71]
	v_mfma_f32_16x16x32_bf16 v[68:71], v[162:165], v[196:199], v[24:27]
	v_mfma_f32_16x16x32_bf16 v[24:27], v[182:185], v[192:195], v[64:67]
	v_mfma_f32_16x16x32_bf16 v[64:67], v[188:191], v[196:199], v[24:27]
	v_mfma_f32_16x16x32_bf16 v[24:27], v[158:161], v[200:203], v[52:55]
	v_mfma_f32_16x16x32_bf16 v[52:55], v[162:165], v[204:207], v[24:27]
	v_mfma_f32_16x16x32_bf16 v[24:27], v[182:185], v[200:203], v[48:51]
	v_mfma_f32_16x16x32_bf16 v[48:51], v[188:191], v[204:207], v[24:27]
	v_mfma_f32_16x16x32_bf16 v[24:27], v[158:161], v[208:211], v[36:39]
	v_mfma_f32_16x16x32_bf16 v[36:39], v[162:165], v[212:215], v[24:27]
	v_mfma_f32_16x16x32_bf16 v[24:27], v[182:185], v[208:211], v[32:35]
	v_mfma_f32_16x16x32_bf16 v[20:23], v[158:161], v[216:219], v[20:23]
	v_mfma_f32_16x16x32_bf16 v[16:19], v[182:185], v[216:219], v[16:19]
	v_mfma_f32_16x16x32_bf16 v[32:35], v[188:191], v[212:215], v[24:27]
	v_mfma_f32_16x16x32_bf16 v[20:23], v[162:165], v[220:223], v[20:23]
	v_mfma_f32_16x16x32_bf16 v[16:19], v[188:191], v[220:223], v[16:19]
	s_setprio 0
	s_barrier
	s_add_i32 s58, 0, 0x18000
	s_add_i32 s59, 0, 0x1c000
	v_add_u32_e32 v140, s58, v169
	v_add_u32_e32 v152, s59, v169
	ds_read_b128 v[24:27], v140
	ds_read_b128 v[28:31], v140 offset:1024
	ds_read_b128 v[136:139], v140 offset:2048
	ds_read_b128 v[140:143], v140 offset:3072
	ds_read_b128 v[158:161], v152
	ds_read_b128 v[162:165], v152 offset:1024
	ds_read_b128 v[182:185], v152 offset:2048
	ds_read_b128 v[188:191], v152 offset:3072
	s_add_u32 s52, s56, 0x40000
	s_addc_u32 s53, s57, 0
	s_mov_b32 m0, s88
	ds_read_b128 v[192:195], v176 offset:32768
	ds_read_b128 v[196:199], v176 offset:33792
	ds_read_b128 v[200:203], v176 offset:34816
	ds_read_b128 v[204:207], v176 offset:35840
	ds_read_b128 v[208:211], v176 offset:36864
	ds_read_b128 v[212:215], v176 offset:37888
	ds_read_b128 v[216:219], v176 offset:38912
	ds_read_b128 v[220:223], v176 offset:39936
	global_load_lds_dwordx4 v144, s[52:53]
	s_mov_b32 m0, s89
	s_nop 0
	global_load_lds_dwordx4 v148, s[52:53]
	s_waitcnt vmcnt(8)
	s_waitcnt lgkmcnt(0)
	s_barrier
; template <class Epi, class Sched, bool ALIGN_EPI = false, bool SP2 = false, bool HS = false>
; __device__ __forceinline__ void gemm_phase(PG8_LAS unsigned char* lds, const Gemm g, const Sched& S, const Epi& E) {
;     ...
;         for (int t = 0; t < nt; t += 2) {
;             if constexpr (HS) {
;                 if (t == 4 || t == 8 || t == 12) {
;                     const PG8_LAS float* tab = (const PG8_LAS float*)(lds + 147456);
;                     const int hj = (t >> 2) - 1;
; #pragma unroll
;                     for (int a = 0; a < 2; ++a)
; #pragma unroll
;                         for (int m = 0; m < 4; ++m) {
;                             const float s = tab[(a * 128 + wr * 64 + m * 16 + fr) * 4 + hj];
; #pragma unroll
;                             for (int b = 0; b < 2; ++b)
; #pragma unroll
;                                 for (int n = 0; n < 2; ++n) acc[a][b][m][n] = acc[a][b][m][n] * s;
;                         }
;                 }
;             }
;             const bool last = (t == nt - 2);
;             const char* a1 = cA + (size_t)(t + 1) * kstep;
;             const char* a2 = last ? nA : cA + (size_t)(t + 2) * kstep; const char* b2 = last ? nB : cB + (size_t)(t + 2) * kstep;
;             const char* a3 = a2 + kstep; const char* b3 = b2 + kstep;
;             if (last && has_next) S.a_ready(nxt);
;             if constexpr (SP2) {
;             PG8_LDB(B0, 0, 0); PG8_LDB(B1, 0, 1); PG8_SCHED; PG8_LDA(At, 0, 0); PG8_STAGE(PG8_SA(1, 1), a1 + hstep, voffA);
;             PG8_WAIT_V(8); PG8_WAIT_L(0); PG8_BAR; PG8_MMA(0, 0, At, B0); PG8_MMA(0, 1, At, B1); PG8_BAR; PG8_SCHED;
;             PG8_LDA(At, 0, 1); PG8_STAGE(PG8_SB(0, 0), b2, voffB); PG8_STAGE(PG8_SB(0, 1), b2 + hstep, voffB); PG8_STAGE(PG8_SA(0, 0), a2, voffA);
;             PG8_WAIT_V(8); PG8_WAIT_L(0); PG8_BAR; PG8_MMA(1, 0, At, B0); PG8_MMA(1, 1, At, B1); PG8_BAR; PG8_SCHED;
;             PG8_LDB(B0, 1, 0); PG8_LDB(B1, 1, 1); PG8_SCHED; PG8_LDA(At, 1, 0); PG8_STAGE(PG8_SA(0, 1), a2 + hstep, voffA);
;             PG8_WAIT_V(8); PG8_WAIT_L(0); PG8_BAR; PG8_MMA(0, 0, At, B0); PG8_MMA(0, 1, At, B1); PG8_BAR; PG8_SCHED;
;             PG8_LDA(At, 1, 1); PG8_STAGE(PG8_SB(1, 0), b3, voffB); PG8_STAGE(PG8_SB(1, 1), b3 + hstep, voffB); PG8_STAGE(PG8_SA(1, 0), a3, voffA);
;             PG8_WAIT_V(8); PG8_WAIT_L(0); PG8_BAR; PG8_MMA(1, 0, At, B0); PG8_MMA(1, 1, At, B1); PG8_BAR; PG8_SCHED;
	s_setprio 1
	s_waitcnt lgkmcnt(0)
	v_mfma_f32_16x16x32_bf16 v[8:11], v[24:27], v[192:195], v[8:11]
	v_mfma_f32_16x16x32_bf16 v[0:3], v[136:139], v[192:195], v[0:3]
	v_mfma_f32_16x16x32_bf16 v[124:127], v[24:27], v[200:203], v[124:127]
	v_mfma_f32_16x16x32_bf16 v[120:123], v[136:139], v[200:203], v[120:123]
	v_mfma_f32_16x16x32_bf16 v[108:111], v[24:27], v[208:211], v[108:111]
	v_mfma_f32_16x16x32_bf16 v[104:107], v[136:139], v[208:211], v[104:107]
	v_mfma_f32_16x16x32_bf16 v[92:95], v[24:27], v[216:219], v[92:95]
	v_mfma_f32_16x16x32_bf16 v[88:91], v[136:139], v[216:219], v[88:91]
	v_mfma_f32_16x16x32_bf16 v[8:11], v[28:31], v[196:199], v[8:11]
	v_mfma_f32_16x16x32_bf16 v[0:3], v[140:143], v[196:199], v[0:3]
	v_mfma_f32_16x16x32_bf16 v[124:127], v[28:31], v[204:207], v[124:127]
	v_mfma_f32_16x16x32_bf16 v[120:123], v[140:143], v[204:207], v[120:123]
	v_mfma_f32_16x16x32_bf16 v[108:111], v[28:31], v[212:215], v[108:111]
	v_mfma_f32_16x16x32_bf16 v[104:107], v[140:143], v[212:215], v[104:107]
	v_mfma_f32_16x16x32_bf16 v[92:95], v[28:31], v[220:223], v[92:95]
	v_mfma_f32_16x16x32_bf16 v[88:91], v[140:143], v[220:223], v[88:91]
	s_setprio 0
	s_setprio 1
	v_mfma_f32_16x16x32_bf16 v[132:135], v[158:161], v[192:195], v[132:135]
	v_mfma_f32_16x16x32_bf16 v[128:131], v[182:185], v[192:195], v[128:131]
	v_mfma_f32_16x16x32_bf16 v[116:119], v[158:161], v[200:203], v[116:119]
	v_mfma_f32_16x16x32_bf16 v[112:115], v[182:185], v[200:203], v[112:115]
	v_mfma_f32_16x16x32_bf16 v[100:103], v[158:161], v[208:211], v[100:103]
	v_mfma_f32_16x16x32_bf16 v[96:99], v[182:185], v[208:211], v[96:99]
	v_mfma_f32_16x16x32_bf16 v[84:87], v[158:161], v[216:219], v[84:87]
	v_mfma_f32_16x16x32_bf16 v[80:83], v[182:185], v[216:219], v[80:83]
	v_mfma_f32_16x16x32_bf16 v[132:135], v[162:165], v[196:199], v[132:135]
	v_mfma_f32_16x16x32_bf16 v[128:131], v[188:191], v[196:199], v[128:131]
	v_mfma_f32_16x16x32_bf16 v[116:119], v[162:165], v[204:207], v[116:119]
	v_mfma_f32_16x16x32_bf16 v[112:115], v[188:191], v[204:207], v[112:115]
	v_mfma_f32_16x16x32_bf16 v[100:103], v[162:165], v[212:215], v[100:103]
	v_mfma_f32_16x16x32_bf16 v[96:99], v[188:191], v[212:215], v[96:99]
	v_mfma_f32_16x16x32_bf16 v[84:87], v[162:165], v[220:223], v[84:87]
	v_mfma_f32_16x16x32_bf16 v[80:83], v[188:191], v[220:223], v[80:83]
	s_setprio 0
	s_barrier
	s_add_i32 s52, s58, s85
	s_mov_b32 m0, s52
	ds_read_b128 v[192:195], v176 offset:49152
	ds_read_b128 v[196:199], v176 offset:50176
	ds_read_b128 v[200:203], v176 offset:51200
	ds_read_b128 v[204:207], v176 offset:52224
	ds_read_b128 v[208:211], v176 offset:53248
	ds_read_b128 v[212:215], v176 offset:54272
	ds_read_b128 v[216:219], v176 offset:55296
	ds_read_b128 v[220:223], v176 offset:56320
	s_add_u32 s98, s10, 0x80
	s_addc_u32 s99, s11, 0
	global_load_lds_dwordx4 v146, s[98:99]
	s_add_i32 m0, s52, 0x2000
	s_add_u32 s10, s10, 0x40080
	s_addc_u32 s11, s11, 0
	s_add_i32 s52, s59, s85
	global_load_lds_dwordx4 v150, s[98:99]
	s_mov_b32 m0, s52
	s_nop 0
	global_load_lds_dwordx4 v146, s[10:11]
	s_add_i32 m0, s52, 0x2000
	s_nop 0
	global_load_lds_dwordx4 v150, s[10:11]
	s_mov_b32 m0, s95
	s_nop 0
	s_add_u32 s98, s56, 0x80
	s_addc_u32 s99, s57, 0
	global_load_lds_dwordx4 v144, s[98:99]
	s_mov_b32 m0, s96
	s_nop 0
	global_load_lds_dwordx4 v148, s[98:99]
	s_waitcnt vmcnt(8)
	s_waitcnt lgkmcnt(0)
	s_barrier
	s_setprio 1
	s_waitcnt lgkmcnt(0)
	v_mfma_f32_16x16x32_bf16 v[76:79], v[24:27], v[192:195], v[76:79]
	v_mfma_f32_16x16x32_bf16 v[60:63], v[24:27], v[200:203], v[60:63]
	v_mfma_f32_16x16x32_bf16 v[44:47], v[24:27], v[208:211], v[44:47]
	v_mfma_f32_16x16x32_bf16 v[4:7], v[24:27], v[216:219], v[4:7]
	v_mfma_f32_16x16x32_bf16 v[76:79], v[28:31], v[196:199], v[76:79]
	v_mfma_f32_16x16x32_bf16 v[72:75], v[136:139], v[192:195], v[72:75]
	v_mfma_f32_16x16x32_bf16 v[60:63], v[28:31], v[204:207], v[60:63]
	v_mfma_f32_16x16x32_bf16 v[56:59], v[136:139], v[200:203], v[56:59]
	v_mfma_f32_16x16x32_bf16 v[44:47], v[28:31], v[212:215], v[44:47]
	v_mfma_f32_16x16x32_bf16 v[40:43], v[136:139], v[208:211], v[40:43]
	v_mfma_f32_16x16x32_bf16 v[28:31], v[28:31], v[220:223], v[4:7]
	v_mfma_f32_16x16x32_bf16 v[4:7], v[136:139], v[216:219], v[12:15]
	v_mfma_f32_16x16x32_bf16 v[72:75], v[140:143], v[196:199], v[72:75]
	v_mfma_f32_16x16x32_bf16 v[56:59], v[140:143], v[204:207], v[56:59]
	v_mfma_f32_16x16x32_bf16 v[40:43], v[140:143], v[212:215], v[40:43]
	v_mfma_f32_16x16x32_bf16 v[24:27], v[140:143], v[220:223], v[4:7]
	s_setprio 0
	s_setprio 1
	v_mfma_f32_16x16x32_bf16 v[4:7], v[158:161], v[192:195], v[68:71]
	v_mfma_f32_16x16x32_bf16 v[68:71], v[162:165], v[196:199], v[4:7]
	v_mfma_f32_16x16x32_bf16 v[4:7], v[182:185], v[192:195], v[64:67]
	v_mfma_f32_16x16x32_bf16 v[64:67], v[188:191], v[196:199], v[4:7]
	v_mfma_f32_16x16x32_bf16 v[4:7], v[158:161], v[200:203], v[52:55]
	v_mfma_f32_16x16x32_bf16 v[52:55], v[162:165], v[204:207], v[4:7]
	v_mfma_f32_16x16x32_bf16 v[4:7], v[182:185], v[200:203], v[48:51]
	v_mfma_f32_16x16x32_bf16 v[48:51], v[188:191], v[204:207], v[4:7]
	v_mfma_f32_16x16x32_bf16 v[4:7], v[158:161], v[208:211], v[36:39]
	v_mfma_f32_16x16x32_bf16 v[36:39], v[162:165], v[212:215], v[4:7]
	v_mfma_f32_16x16x32_bf16 v[4:7], v[182:185], v[208:211], v[32:35]
	v_mfma_f32_16x16x32_bf16 v[32:35], v[188:191], v[212:215], v[4:7]
	v_mfma_f32_16x16x32_bf16 v[4:7], v[158:161], v[216:219], v[20:23]
	v_mfma_f32_16x16x32_bf16 v[20:23], v[162:165], v[220:223], v[4:7]
	v_mfma_f32_16x16x32_bf16 v[4:7], v[182:185], v[216:219], v[16:19]
	v_mfma_f32_16x16x32_bf16 v[16:19], v[188:191], v[220:223], v[4:7]
	s_setprio 0
	s_barrier
	s_add_i32 s45, s45, 2
	s_add_u32 s8, s8, 0x100
	s_addc_u32 s9, s9, 0
	s_add_u32 s7, s7, 0x100
	s_addc_u32 s37, s37, 0
	s_cmp_gt_u32 s45, 13
	s_cbranch_scc0 .LBB0_262
	s_and_b64 vcc, exec, s[16:17]
	s_cbranch_vccz .LBB0_265
	s_barrier
